# phase B epilogue: packed-layout address prep sunk behind its wave-uniform branch (skipped on 28 of 36 N-tiles)
# baseline (speedup 1.0000x reference)
;     __device__ __forceinline__ void operator()(const f32x4 (&acc)[2][2][4][2], const Unit& u, int wr, int wc, int fr, int fq) const {
;     ...
;                     if (kvt) { const int c = col0 + bj * HALF; int hd, off;
;                         if (colt < 2048) { const int cp = c - 1024, d = cp & 63; hd = (cp >> 6) & 7; off = (cp >> 9) * 8192 + kv * 128 + (((d >> 3) ^ ((kv >> 1) & 7)) << 4); }
;                         else { const int cp = c - 2048, d = cp & 127; hd = cp >> 7; off = 16384 + (d >> 5) * 4096 + kv * 64 + (((d >> 3) & 3) << 4); }
;                         *(u32x4*)(KV + ((size_t)((((seq << 3) + hd) << (sshift - 6)) + tile) << 15) + off) = w; }
.LBB0_96:
	s_andn2_b64 vcc, exec, s[8:9]
	s_cbranch_vccnz .LBB0_98
	v_and_b32_e32 v127, s45, v130
	v_lshrrev_b32_e32 v129, 6, v127
	v_lshrrev_b32_e32 v127, 1, v127
	s_lshl_b32 s55, s55, 12
	v_xor_b32_e32 v127, v127, v146
	s_and_b32 s55, s55, 0x6000
	v_lshlrev_b32_e32 v127, 4, v127
	s_addk_i32 s55, 0xc000
	v_and_b32_e32 v127, 0x70, v127
	v_ashrrev_i32_e32 v126, s22, v130
	v_or3_b32 v127, v127, v148, s55
	v_lshlrev_b32_e32 v154, 3, v126
	v_cndmask_b32_e64 v126, v147, v127, s[6:7]
	v_lshrrev_b32_e32 v128, 6, v134
	v_ashrrev_i32_e32 v127, 31, v126
	s_add_i32 s8, s54, 0xfffff800
	s_ashr_i32 s8, s8, 7
	v_and_b32_e32 v139, 5, v128
	v_mov_b32_e32 v155, s8
	v_cndmask_b32_e64 v139, v155, v139, s[6:7]
	v_add_u32_e32 v139, v154, v139
	v_lshl_add_u32 v156, v139, s46, v129
	v_ashrrev_i32_e32 v157, 31, v156
	v_lshlrev_b64 v[156:157], 15, v[156:157]
	v_lshl_add_u64 v[156:157], s[74:75], 0, v[156:157]
	v_lshl_add_u64 v[156:157], v[156:157], 0, v[126:127]
	global_store_dwordx4 v[156:157], v[122:125], off

;     __device__ __forceinline__ void operator()(const f32x4 (&acc)[2][2][4][2], const Unit& u, int wr, int wc, int fr, int fq) const {
;     ...
;                     if (kvt) { const int c = col0 + bj * HALF; int hd, off;
;                         if (colt < 2048) { const int cp = c - 1024, d = cp & 63; hd = (cp >> 6) & 7; off = (cp >> 9) * 8192 + kv * 128 + (((d >> 3) ^ ((kv >> 1) & 7)) << 4); }
;                         else { const int cp = c - 2048, d = cp & 127; hd = cp >> 7; off = 16384 + (d >> 5) * 4096 + kv * 64 + (((d >> 3) & 3) << 4); }
;                         *(u32x4*)(KV + ((size_t)((((seq << 3) + hd) << (sshift - 6)) + tile) << 15) + off) = w; }
.LBB0_104:
	s_andn2_b64 vcc, exec, s[26:27]
	s_cbranch_vccnz .LBB0_106
	v_bitop3_b32 v111, v130, s45, 16 bitop3:0xc8
	v_lshrrev_b32_e32 v112, 6, v111
	v_lshrrev_b32_e32 v111, 1, v111
	v_xor_b32_e32 v111, v111, v146
	v_bitop3_b32 v113, v130, 31, 16 bitop3:0xc8
	v_lshlrev_b32_e32 v111, 4, v111
	v_lshl_or_b32 v117, v113, 6, v145
	v_lshlrev_b32_e32 v113, 7, v113
	v_and_b32_e32 v111, 0x70, v111
	v_ashrrev_i32_e32 v110, s22, v118
	v_or3_b32 v111, v111, v113, s55
	v_lshlrev_b32_e32 v113, 3, v110
	v_cndmask_b32_e64 v110, v117, v111, s[6:7]
	v_ashrrev_i32_e32 v111, 31, v110
	s_add_i32 s26, s54, 0xfffff800
	s_ashr_i32 s26, s26, 7
	v_and_b32_e32 v117, 5, v128
	v_mov_b32_e32 v118, s26
	v_cndmask_b32_e64 v117, v118, v117, s[6:7]
	v_add_u32_e32 v117, v113, v117
	v_lshl_add_u32 v118, v117, s46, v112
	v_ashrrev_i32_e32 v119, 31, v118
	v_lshlrev_b64 v[118:119], 15, v[118:119]
	v_lshl_add_u64 v[118:119], s[74:75], 0, v[118:119]
	v_lshl_add_u64 v[118:119], v[118:119], 0, v[110:111]
	global_store_dwordx4 v[118:119], v[106:109], off

;     __device__ __forceinline__ void operator()(const f32x4 (&acc)[2][2][4][2], const Unit& u, int wr, int wc, int fr, int fq) const {
;     ...
;                     if (kvt) { const int c = col0 + bj * HALF; int hd, off;
;                         if (colt < 2048) { const int cp = c - 1024, d = cp & 63; hd = (cp >> 6) & 7; off = (cp >> 9) * 8192 + kv * 128 + (((d >> 3) ^ ((kv >> 1) & 7)) << 4); }
;                         else { const int cp = c - 2048, d = cp & 127; hd = cp >> 7; off = 16384 + (d >> 5) * 4096 + kv * 64 + (((d >> 3) & 3) << 4); }
;                         *(u32x4*)(KV + ((size_t)((((seq << 3) + hd) << (sshift - 6)) + tile) << 15) + off) = w; }
.LBB0_112:
	s_andn2_b64 vcc, exec, s[26:27]
	s_cbranch_vccnz .LBB0_114
	v_bitop3_b32 v95, v130, s45, 32 bitop3:0xc8
	v_lshrrev_b32_e32 v96, 6, v95
	v_lshrrev_b32_e32 v95, 1, v95
	v_xor_b32_e32 v95, v95, v146
	v_bitop3_b32 v97, v130, 47, 32 bitop3:0xc8
	v_lshlrev_b32_e32 v95, 4, v95
	v_lshl_or_b32 v101, v97, 6, v145
	v_lshlrev_b32_e32 v97, 7, v97
	v_and_b32_e32 v95, 0x70, v95
	v_ashrrev_i32_e32 v94, s22, v102
	v_or3_b32 v95, v95, v97, s55
	v_lshlrev_b32_e32 v97, 3, v94
	v_cndmask_b32_e64 v94, v101, v95, s[6:7]
	v_ashrrev_i32_e32 v95, 31, v94
	s_add_i32 s26, s54, 0xfffff800
	s_ashr_i32 s26, s26, 7
	v_and_b32_e32 v101, 5, v128
	v_mov_b32_e32 v102, s26
	v_cndmask_b32_e64 v101, v102, v101, s[6:7]
	v_add_u32_e32 v101, v97, v101
	v_lshl_add_u32 v102, v101, s46, v96
	v_ashrrev_i32_e32 v103, 31, v102
	v_lshlrev_b64 v[102:103], 15, v[102:103]
	v_lshl_add_u64 v[102:103], s[74:75], 0, v[102:103]
	v_lshl_add_u64 v[102:103], v[102:103], 0, v[94:95]
	global_store_dwordx4 v[102:103], v[90:93], off

;     __device__ __forceinline__ void operator()(const f32x4 (&acc)[2][2][4][2], const Unit& u, int wr, int wc, int fr, int fq) const {
;     ...
;                     if (kvt) { const int c = col0 + bj * HALF; int hd, off;
;                         if (colt < 2048) { const int cp = c - 1024, d = cp & 63; hd = (cp >> 6) & 7; off = (cp >> 9) * 8192 + kv * 128 + (((d >> 3) ^ ((kv >> 1) & 7)) << 4); }
;                         else { const int cp = c - 2048, d = cp & 127; hd = cp >> 7; off = 16384 + (d >> 5) * 4096 + kv * 64 + (((d >> 3) & 3) << 4); }
;                         *(u32x4*)(KV + ((size_t)((((seq << 3) + hd) << (sshift - 6)) + tile) << 15) + off) = w; }
.LBB0_120:
	s_andn2_b64 vcc, exec, s[26:27]
	s_cbranch_vccnz .LBB0_122
	v_bitop3_b32 v79, v130, s45, 48 bitop3:0xc8
	v_lshrrev_b32_e32 v80, 6, v79
	v_lshrrev_b32_e32 v79, 1, v79
	v_xor_b32_e32 v79, v79, v146
	v_bitop3_b32 v81, v130, 63, 48 bitop3:0xc8
	v_lshlrev_b32_e32 v79, 4, v79
	v_lshl_or_b32 v85, v81, 6, v145
	v_lshlrev_b32_e32 v81, 7, v81
	v_and_b32_e32 v79, 0x70, v79
	v_ashrrev_i32_e32 v78, s22, v86
	v_or3_b32 v79, v79, v81, s55
	v_lshlrev_b32_e32 v81, 3, v78
	v_cndmask_b32_e64 v78, v85, v79, s[6:7]
	v_ashrrev_i32_e32 v79, 31, v78
	s_add_i32 s26, s54, 0xfffff800
	s_ashr_i32 s26, s26, 7
	v_and_b32_e32 v85, 5, v128
	v_mov_b32_e32 v86, s26
	v_cndmask_b32_e64 v85, v86, v85, s[6:7]
	v_add_u32_e32 v85, v81, v85
	v_lshl_add_u32 v86, v85, s46, v80
	v_ashrrev_i32_e32 v87, 31, v86
	v_lshlrev_b64 v[86:87], 15, v[86:87]
	v_lshl_add_u64 v[86:87], s[74:75], 0, v[86:87]
	v_lshl_add_u64 v[86:87], v[86:87], 0, v[78:79]
	global_store_dwordx4 v[86:87], v[74:77], off

;     __device__ __forceinline__ void operator()(const f32x4 (&acc)[2][2][4][2], const Unit& u, int wr, int wc, int fr, int fq) const {
;     ...
;                     if (kvt) { const int c = col0 + bj * HALF; int hd, off;
;                         if (colt < 2048) { const int cp = c - 1024, d = cp & 63; hd = (cp >> 6) & 7; off = (cp >> 9) * 8192 + kv * 128 + (((d >> 3) ^ ((kv >> 1) & 7)) << 4); }
;                         else { const int cp = c - 2048, d = cp & 127; hd = cp >> 7; off = 16384 + (d >> 5) * 4096 + kv * 64 + (((d >> 3) & 3) << 4); }
;                         *(u32x4*)(KV + ((size_t)((((seq << 3) + hd) << (sshift - 6)) + tile) << 15) + off) = w; }
.LBB0_128:
	s_andn2_b64 vcc, exec, s[26:27]
	s_cbranch_vccnz .LBB0_130
	v_and_b32_e32 v63, s45, v69
	v_lshrrev_b32_e32 v64, 6, v63
	v_lshrrev_b32_e32 v63, 1, v63
	v_xor_b32_e32 v63, v63, v146
	v_lshlrev_b32_e32 v63, 4, v63
	v_and_b32_e32 v63, 0x70, v63
	v_ashrrev_i32_e32 v62, s22, v69
	v_or3_b32 v63, v63, v148, s55
	v_lshlrev_b32_e32 v65, 3, v62
	v_cndmask_b32_e64 v62, v147, v63, s[6:7]
	v_ashrrev_i32_e32 v63, 31, v62
	s_add_i32 s26, s54, 0xfffff800
	s_ashr_i32 s26, s26, 7
	v_and_b32_e32 v69, 5, v128
	v_mov_b32_e32 v70, s26
	v_cndmask_b32_e64 v69, v70, v69, s[6:7]
	v_add_u32_e32 v69, v65, v69
	v_lshl_add_u32 v70, v69, s46, v64
	v_ashrrev_i32_e32 v71, 31, v70
	v_lshlrev_b64 v[70:71], 15, v[70:71]
	v_lshl_add_u64 v[70:71], s[74:75], 0, v[70:71]
	v_lshl_add_u64 v[70:71], v[70:71], 0, v[62:63]
	global_store_dwordx4 v[70:71], v[58:61], off

;     __device__ __forceinline__ void operator()(const f32x4 (&acc)[2][2][4][2], const Unit& u, int wr, int wc, int fr, int fq) const {
;     ...
;                     if (kvt) { const int c = col0 + bj * HALF; int hd, off;
;                         if (colt < 2048) { const int cp = c - 1024, d = cp & 63; hd = (cp >> 6) & 7; off = (cp >> 9) * 8192 + kv * 128 + (((d >> 3) ^ ((kv >> 1) & 7)) << 4); }
;                         else { const int cp = c - 2048, d = cp & 127; hd = cp >> 7; off = 16384 + (d >> 5) * 4096 + kv * 64 + (((d >> 3) & 3) << 4); }
;                         *(u32x4*)(KV + ((size_t)((((seq << 3) + hd) << (sshift - 6)) + tile) << 15) + off) = w; }
.LBB0_136:
	s_andn2_b64 vcc, exec, s[26:27]
	s_cbranch_vccnz .LBB0_138
	v_and_b32_e32 v47, s45, v53
	v_lshrrev_b32_e32 v48, 6, v47
	v_lshrrev_b32_e32 v47, 1, v47
	v_xor_b32_e32 v47, v47, v146
	v_and_b32_e32 v49, 31, v53
	v_lshlrev_b32_e32 v47, 4, v47
	v_ashrrev_i32_e32 v46, s22, v53
	v_lshl_or_b32 v53, v49, 6, v145
	v_lshlrev_b32_e32 v49, 7, v49
	v_and_b32_e32 v47, 0x70, v47
	v_or3_b32 v47, v47, v49, s55
	v_lshlrev_b32_e32 v49, 3, v46
	v_cndmask_b32_e64 v46, v53, v47, s[6:7]
	v_ashrrev_i32_e32 v47, 31, v46
	s_add_i32 s26, s54, 0xfffff800
	s_ashr_i32 s26, s26, 7
	v_and_b32_e32 v53, 5, v128
	v_mov_b32_e32 v54, s26
	v_cndmask_b32_e64 v53, v54, v53, s[6:7]
	v_add_u32_e32 v53, v49, v53
	v_lshl_add_u32 v54, v53, s46, v48
	v_ashrrev_i32_e32 v55, 31, v54
	v_lshlrev_b64 v[54:55], 15, v[54:55]
	v_lshl_add_u64 v[54:55], s[74:75], 0, v[54:55]
	v_lshl_add_u64 v[54:55], v[54:55], 0, v[46:47]
	global_store_dwordx4 v[54:55], v[42:45], off

;     __device__ __forceinline__ void operator()(const f32x4 (&acc)[2][2][4][2], const Unit& u, int wr, int wc, int fr, int fq) const {
;     ...
;                     if (kvt) { const int c = col0 + bj * HALF; int hd, off;
;                         if (colt < 2048) { const int cp = c - 1024, d = cp & 63; hd = (cp >> 6) & 7; off = (cp >> 9) * 8192 + kv * 128 + (((d >> 3) ^ ((kv >> 1) & 7)) << 4); }
;                         else { const int cp = c - 2048, d = cp & 127; hd = cp >> 7; off = 16384 + (d >> 5) * 4096 + kv * 64 + (((d >> 3) & 3) << 4); }
;                         *(u32x4*)(KV + ((size_t)((((seq << 3) + hd) << (sshift - 6)) + tile) << 15) + off) = w; }
.LBB0_144:
	s_andn2_b64 vcc, exec, s[26:27]
	s_cbranch_vccnz .LBB0_146
	v_and_b32_e32 v31, s45, v37
	v_lshrrev_b32_e32 v32, 6, v31
	v_lshrrev_b32_e32 v31, 1, v31
	v_xor_b32_e32 v31, v31, v146
	v_and_b32_e32 v33, 47, v37
	v_lshlrev_b32_e32 v31, 4, v31
	v_ashrrev_i32_e32 v30, s22, v37
	v_lshl_or_b32 v37, v33, 6, v145
	v_lshlrev_b32_e32 v33, 7, v33
	v_and_b32_e32 v31, 0x70, v31
	v_or3_b32 v31, v31, v33, s55
	v_lshlrev_b32_e32 v33, 3, v30
	v_cndmask_b32_e64 v30, v37, v31, s[6:7]
	v_ashrrev_i32_e32 v31, 31, v30
	s_add_i32 s26, s54, 0xfffff800
	s_ashr_i32 s26, s26, 7
	v_and_b32_e32 v37, 5, v128
	v_mov_b32_e32 v38, s26
	v_cndmask_b32_e64 v37, v38, v37, s[6:7]
	v_add_u32_e32 v37, v33, v37
	v_lshl_add_u32 v38, v37, s46, v32
	v_ashrrev_i32_e32 v39, 31, v38
	v_lshlrev_b64 v[38:39], 15, v[38:39]
	v_lshl_add_u64 v[38:39], s[74:75], 0, v[38:39]
	v_lshl_add_u64 v[38:39], v[38:39], 0, v[30:31]
	global_store_dwordx4 v[38:39], v[26:29], off

;     __device__ __forceinline__ void operator()(const f32x4 (&acc)[2][2][4][2], const Unit& u, int wr, int wc, int fr, int fq) const {
;     ...
;                     if (kvt) { const int c = col0 + bj * HALF; int hd, off;
;                         if (colt < 2048) { const int cp = c - 1024, d = cp & 63; hd = (cp >> 6) & 7; off = (cp >> 9) * 8192 + kv * 128 + (((d >> 3) ^ ((kv >> 1) & 7)) << 4); }
;                         else { const int cp = c - 2048, d = cp & 127; hd = cp >> 7; off = 16384 + (d >> 5) * 4096 + kv * 64 + (((d >> 3) & 3) << 4); }
;                         *(u32x4*)(KV + ((size_t)((((seq << 3) + hd) << (sshift - 6)) + tile) << 15) + off) = w; }
.LBB0_152:
	s_andn2_b64 vcc, exec, s[26:27]
	s_cbranch_vccnz .LBB0_154
	v_and_b32_e32 v15, s45, v21
	v_lshrrev_b32_e32 v16, 6, v15
	v_lshrrev_b32_e32 v15, 1, v15
	v_xor_b32_e32 v15, v15, v146
	v_and_b32_e32 v17, 63, v21
	v_lshlrev_b32_e32 v15, 4, v15
	v_ashrrev_i32_e32 v14, s22, v21
	v_lshl_or_b32 v21, v17, 6, v145
	v_lshlrev_b32_e32 v17, 7, v17
	v_and_b32_e32 v15, 0x70, v15
	v_or3_b32 v15, v15, v17, s55
	v_lshlrev_b32_e32 v17, 3, v14
	v_cndmask_b32_e64 v14, v21, v15, s[6:7]
	v_ashrrev_i32_e32 v15, 31, v14
	s_add_i32 s26, s54, 0xfffff800
	s_ashr_i32 s26, s26, 7
	v_and_b32_e32 v21, 5, v128
	v_mov_b32_e32 v22, s26
	v_cndmask_b32_e64 v21, v22, v21, s[6:7]
	v_add_u32_e32 v21, v17, v21
	v_lshl_add_u32 v22, v21, s46, v16
	v_ashrrev_i32_e32 v23, 31, v22
	v_lshlrev_b64 v[22:23], 15, v[22:23]
	v_lshl_add_u64 v[22:23], s[74:75], 0, v[22:23]
	v_lshl_add_u64 v[22:23], v[22:23], 0, v[14:15]
	global_store_dwordx4 v[22:23], v[10:13], off
